# band attention: all 16 V-fragment transpose reads hoisted above the softmax into fresh registers (LDS latency overlaps softmax VALU; one wait before PV MFMAs)
# baseline (speedup 1.0000x reference)
.LBB0_459:
	ds_read_b64_tr_b16 v[188:189], v153 offset:9216
	ds_read_b64_tr_b16 v[190:191], v153 offset:9984
	ds_read_b64_tr_b16 v[192:193], v153 offset:9280
	ds_read_b64_tr_b16 v[194:195], v153 offset:10048
	ds_read_b64_tr_b16 v[196:197], v153 offset:12288
	ds_read_b64_tr_b16 v[198:199], v153 offset:13056
	ds_read_b64_tr_b16 v[200:201], v153 offset:12352
	ds_read_b64_tr_b16 v[202:203], v153 offset:13120
	ds_read_b64_tr_b16 v[204:205], v153 offset:15360
	ds_read_b64_tr_b16 v[206:207], v153 offset:16128
	ds_read_b64_tr_b16 v[208:209], v153 offset:15424
	ds_read_b64_tr_b16 v[210:211], v153 offset:16192
	ds_read_b64_tr_b16 v[212:213], v153 offset:18432
	ds_read_b64_tr_b16 v[214:215], v153 offset:19200
	ds_read_b64_tr_b16 v[216:217], v153 offset:18496
	ds_read_b64_tr_b16 v[218:219], v153 offset:19264
	s_nop 0
	v_max_f32_e32 v2, v147, v147
	s_nop 2
	v_max_f32_e32 v50, v146, v146
	v_max_f32_e32 v2, v50, v2
	v_max3_f32 v2, v2, v144, v145
	v_max3_f32 v2, v2, v142, v143
	v_max3_f32 v2, v2, v140, v141
	v_max3_f32 v2, v2, v138, v139
	v_max3_f32 v2, v2, v134, v135
	v_max3_f32 v2, v2, v130, v131
	v_max3_f32 v2, v2, v16, v17
	v_max3_f32 v2, v2, v136, v137
	v_max3_f32 v2, v2, v132, v133
	v_max3_f32 v2, v2, v14, v15
	v_max3_f32 v2, v2, v12, v13
	v_max3_f32 v2, v2, v10, v11
	v_max3_f32 v2, v2, v8, v9
	v_max3_f32 v2, v2, v6, v7
	v_max3_f32 v2, v2, v4, v5
	v_mov_b32_e32 v50, v2
	s_nop 1
	v_permlane32_swap_b32_e32 v50, v2
	v_max3_f32 v50, v173, v2, v50
	v_sub_f32_e32 v2, v173, v50
	v_exp_f32_e32 v2, v2
	s_nop 0
	v_cmp_neq_f32_e32 vcc, 1.0, v2
	s_cbranch_vccz .LBB0_461
	v_pk_mul_f32 v[48:49], v[48:49], v[2:3] op_sel_hi:[1,0]
	v_pk_mul_f32 v[46:47], v[46:47], v[2:3] op_sel_hi:[1,0]
	v_pk_mul_f32 v[44:45], v[44:45], v[2:3] op_sel_hi:[1,0]
	v_pk_mul_f32 v[42:43], v[42:43], v[2:3] op_sel_hi:[1,0]
	v_pk_mul_f32 v[40:41], v[40:41], v[2:3] op_sel_hi:[1,0]
	v_pk_mul_f32 v[38:39], v[38:39], v[2:3] op_sel_hi:[1,0]
	v_pk_mul_f32 v[36:37], v[36:37], v[2:3] op_sel_hi:[1,0]
	v_pk_mul_f32 v[34:35], v[34:35], v[2:3] op_sel_hi:[1,0]
	v_pk_mul_f32 v[32:33], v[32:33], v[2:3] op_sel_hi:[1,0]
	v_pk_mul_f32 v[30:31], v[30:31], v[2:3] op_sel_hi:[1,0]
	v_pk_mul_f32 v[28:29], v[28:29], v[2:3] op_sel_hi:[1,0]
	v_pk_mul_f32 v[26:27], v[26:27], v[2:3] op_sel_hi:[1,0]
	v_pk_mul_f32 v[24:25], v[24:25], v[2:3] op_sel_hi:[1,0]
	v_pk_mul_f32 v[22:23], v[22:23], v[2:3] op_sel_hi:[1,0]
	v_pk_mul_f32 v[20:21], v[20:21], v[2:3] op_sel_hi:[1,0]
	v_pk_mul_f32 v[18:19], v[18:19], v[2:3] op_sel_hi:[1,0]
.LBB0_461:
	v_pk_add_f32 v[146:147], v[146:147], v[50:51] op_sel_hi:[1,0] neg_lo:[0,1] neg_hi:[0,1]
	v_pk_add_f32 v[144:145], v[144:145], v[50:51] op_sel_hi:[1,0] neg_lo:[0,1] neg_hi:[0,1]
	v_pk_add_f32 v[142:143], v[142:143], v[50:51] op_sel_hi:[1,0] neg_lo:[0,1] neg_hi:[0,1]
	v_pk_add_f32 v[140:141], v[140:141], v[50:51] op_sel_hi:[1,0] neg_lo:[0,1] neg_hi:[0,1]
	v_pk_add_f32 v[138:139], v[138:139], v[50:51] op_sel_hi:[1,0] neg_lo:[0,1] neg_hi:[0,1]
	v_pk_add_f32 v[134:135], v[134:135], v[50:51] op_sel_hi:[1,0] neg_lo:[0,1] neg_hi:[0,1]
	v_pk_add_f32 v[130:131], v[130:131], v[50:51] op_sel_hi:[1,0] neg_lo:[0,1] neg_hi:[0,1]
	v_pk_add_f32 v[16:17], v[16:17], v[50:51] op_sel_hi:[1,0] neg_lo:[0,1] neg_hi:[0,1]
	v_pk_add_f32 v[136:137], v[136:137], v[50:51] op_sel_hi:[1,0] neg_lo:[0,1] neg_hi:[0,1]
	v_pk_add_f32 v[132:133], v[132:133], v[50:51] op_sel_hi:[1,0] neg_lo:[0,1] neg_hi:[0,1]
	v_pk_add_f32 v[14:15], v[14:15], v[50:51] op_sel_hi:[1,0] neg_lo:[0,1] neg_hi:[0,1]
	v_pk_add_f32 v[12:13], v[12:13], v[50:51] op_sel_hi:[1,0] neg_lo:[0,1] neg_hi:[0,1]
	v_pk_add_f32 v[10:11], v[10:11], v[50:51] op_sel_hi:[1,0] neg_lo:[0,1] neg_hi:[0,1]
	v_pk_add_f32 v[8:9], v[8:9], v[50:51] op_sel_hi:[1,0] neg_lo:[0,1] neg_hi:[0,1]
	v_pk_add_f32 v[6:7], v[6:7], v[50:51] op_sel_hi:[1,0] neg_lo:[0,1] neg_hi:[0,1]
	v_pk_add_f32 v[4:5], v[4:5], v[50:51] op_sel_hi:[1,0] neg_lo:[0,1] neg_hi:[0,1]
	v_exp_f32_e32 v52, v146
	v_exp_f32_e32 v53, v147
	v_exp_f32_e32 v54, v144
	v_exp_f32_e32 v55, v145
	v_exp_f32_e32 v56, v142
	v_exp_f32_e32 v57, v143
	v_pk_add_f32 v[80:81], v[52:53], v[54:55]
	v_exp_f32_e32 v58, v140
	v_exp_f32_e32 v59, v141
	v_pk_add_f32 v[80:81], v[80:81], v[56:57]
	v_exp_f32_e32 v60, v138
	v_exp_f32_e32 v61, v139
	v_pk_add_f32 v[80:81], v[80:81], v[58:59]
	v_exp_f32_e32 v62, v134
	v_exp_f32_e32 v63, v135
	v_pk_add_f32 v[80:81], v[80:81], v[60:61]
	v_exp_f32_e32 v64, v130
	v_exp_f32_e32 v65, v131
	v_pk_add_f32 v[80:81], v[80:81], v[62:63]
	v_exp_f32_e32 v16, v16
	v_exp_f32_e32 v17, v17
	v_pk_add_f32 v[80:81], v[80:81], v[64:65]
	v_exp_f32_e32 v66, v136
	v_exp_f32_e32 v67, v137
	v_pk_add_f32 v[80:81], v[80:81], v[16:17]
	v_exp_f32_e32 v68, v132
	v_exp_f32_e32 v69, v133
	v_pk_add_f32 v[80:81], v[80:81], v[66:67]
	v_exp_f32_e32 v14, v14
	v_exp_f32_e32 v15, v15
	v_pk_add_f32 v[80:81], v[80:81], v[68:69]
	v_exp_f32_e32 v70, v12
	v_exp_f32_e32 v71, v13
	v_pk_add_f32 v[80:81], v[80:81], v[14:15]
	v_exp_f32_e32 v72, v10
	v_exp_f32_e32 v73, v11
	v_pk_add_f32 v[80:81], v[80:81], v[70:71]
	v_exp_f32_e32 v74, v8
	v_exp_f32_e32 v75, v9
	v_pk_add_f32 v[80:81], v[80:81], v[72:73]
	v_exp_f32_e32 v76, v6
	v_exp_f32_e32 v77, v7
	v_pk_add_f32 v[80:81], v[80:81], v[74:75]
	v_exp_f32_e32 v78, v4
	v_exp_f32_e32 v79, v5
	v_pk_add_f32 v[80:81], v[80:81], v[76:77]
	s_nop 0
	v_pk_add_f32 v[80:81], v[80:81], v[78:79]
	v_add_f32_e32 v80, v80, v81
	v_cvt_pk_bf16_f32 v4, v52, v53
	v_cvt_pk_bf16_f32 v5, v54, v55
	v_cvt_pk_bf16_f32 v6, v56, v57
	v_cvt_pk_bf16_f32 v7, v58, v59
	v_cvt_pk_bf16_f32 v8, v60, v61
	v_cvt_pk_bf16_f32 v9, v62, v63
	v_cvt_pk_bf16_f32 v10, v64, v65
	v_cvt_pk_bf16_f32 v12, v66, v67
	v_fmac_f32_e32 v80, v172, v2
	v_cvt_pk_bf16_f32 v11, v16, v17
	v_cvt_pk_bf16_f32 v13, v68, v69
	v_cvt_pk_bf16_f32 v14, v14, v15
	v_cvt_pk_bf16_f32 v15, v70, v71
	v_cvt_pk_bf16_f32 v68, v72, v73
	v_cvt_pk_bf16_f32 v69, v74, v75
	v_cvt_pk_bf16_f32 v70, v76, v77
	v_cvt_pk_bf16_f32 v71, v78, v79
	s_waitcnt lgkmcnt(0)
	v_mfma_f32_32x32x16_bf16 v[34:49], v[188:191], v[4:7], v[34:49]
	v_mfma_f32_32x32x16_bf16 v[18:33], v[192:195], v[4:7], v[18:33]
	v_mfma_f32_32x32x16_bf16 v[34:49], v[196:199], v[8:11], v[34:49]
	v_mfma_f32_32x32x16_bf16 v[18:33], v[200:203], v[8:11], v[18:33]
	v_mfma_f32_32x32x16_bf16 v[34:49], v[204:207], v[12:15], v[34:49]
	v_mfma_f32_32x32x16_bf16 v[18:33], v[208:211], v[12:15], v[18:33]
	v_mfma_f32_32x32x16_bf16 v[34:49], v[212:215], v[68:71], v[34:49]
	v_mfma_f32_32x32x16_bf16 v[18:33], v[216:219], v[68:71], v[18:33]
	v_mov_b32_e32 v172, v80
	s_branch .LBB0_463
